# k26_permlane
# speedup vs baseline: 1.0086x; 1.0030x over previous
; template <bool MLA>
; DI void attn_task(const Params& p, char* smem, int b, int head, int qt) {
;     ...
;       float mx = s[0][0];
; #pragma unroll
;       for (int k2 = 0; k2 < 2; ++k2)
; #pragma unroll
;         for (int i = 0; i < 16; ++i) mx = fmaxf(mx, s[k2][i]);
;       mx = fmaxf(mx, __shfl_xor(mx, 32));
;       const float mcand = fmaxf(m, mx);
;       float mn = m;
;       if (__builtin_amdgcn_ballot_w64((mcand - m) > 8.f) != 0ull) {
;         mn = mcand;
;         const float alpha = __builtin_amdgcn_exp2f(m - mn);
;         m = mn;
;         l *= alpha;
; #pragma unroll
;         for (int i = 0; i < 16; ++i) { oacc[0][i] *= alpha; oacc[1][i] *= alpha; }
;       }
.LBB0_366:
	s_or_b64 exec, exec, s[62:63]
	v_max_f32_e32 v106, v49, v49
	v_max_f32_e32 v107, v48, v48
	v_max_f32_e32 v106, v107, v106
	v_max3_f32 v106, v106, v50, v51
	v_max3_f32 v106, v106, v52, v53
	v_max3_f32 v106, v106, v54, v55
	v_max3_f32 v106, v106, v56, v57
	v_max3_f32 v106, v106, v58, v59
	v_max3_f32 v106, v106, v60, v61
	v_max3_f32 v106, v106, v62, v63
	v_max3_f32 v106, v106, v32, v33
	v_max3_f32 v106, v106, v34, v35
	v_max3_f32 v106, v106, v36, v37
	v_max3_f32 v106, v106, v38, v39
	v_max3_f32 v106, v106, v40, v41
	v_max3_f32 v106, v106, v42, v43
	v_max3_f32 v106, v106, v44, v45
	v_max3_f32 v106, v106, v46, v47
	v_mov_b32_e32 v107, v106
	s_nop 1
	v_permlane32_swap_b32_e32 v106, v107
	v_max3_f32 v106, v104, v106, v107
	v_sub_f32_e32 v107, v106, v104
	v_cmp_lt_f32_e32 vcc, s74, v107
	s_cbranch_vccz .LBB0_375
	v_sub_f32_e32 v104, v104, v106
	v_exp_f32_e32 v104, v104
	s_nop 0
	v_pk_mul_f32 v[30:31], v[30:31], v[104:105] op_sel_hi:[1,0]
	v_pk_mul_f32 v[28:29], v[28:29], v[104:105] op_sel_hi:[1,0]
	v_pk_mul_f32 v[26:27], v[26:27], v[104:105] op_sel_hi:[1,0]
	v_pk_mul_f32 v[24:25], v[24:25], v[104:105] op_sel_hi:[1,0]
	v_pk_mul_f32 v[22:23], v[22:23], v[104:105] op_sel_hi:[1,0]
	v_pk_mul_f32 v[20:21], v[20:21], v[104:105] op_sel_hi:[1,0]
	v_pk_mul_f32 v[18:19], v[18:19], v[104:105] op_sel_hi:[1,0]
	v_pk_mul_f32 v[16:17], v[16:17], v[104:105] op_sel_hi:[1,0]
	v_pk_mul_f32 v[14:15], v[14:15], v[104:105] op_sel_hi:[1,0]
	v_pk_mul_f32 v[12:13], v[12:13], v[104:105] op_sel_hi:[1,0]
	v_pk_mul_f32 v[10:11], v[10:11], v[104:105] op_sel_hi:[1,0]
	v_pk_mul_f32 v[8:9], v[8:9], v[104:105] op_sel_hi:[1,0]
	v_pk_mul_f32 v[6:7], v[6:7], v[104:105] op_sel_hi:[1,0]
	v_pk_mul_f32 v[4:5], v[4:5], v[104:105] op_sel_hi:[1,0]
	v_pk_mul_f32 v[2:3], v[2:3], v[104:105] op_sel_hi:[1,0]
	v_pk_mul_f32 v[0:1], v[0:1], v[104:105] op_sel_hi:[1,0]
	v_mul_f32_e32 v105, v105, v104
	v_mov_b32_e32 v104, v106

; template <bool MLA>
; DI void attn_task(const Params& p, char* smem, int b, int head, int qt) {
;     ...
;       float mx = s[0][0];
; #pragma unroll
;       for (int k2 = 0; k2 < 2; ++k2)
; #pragma unroll
;         for (int i = 0; i < 16; ++i) mx = fmaxf(mx, s[k2][i]);
;       mx = fmaxf(mx, __shfl_xor(mx, 32));
;       const float mcand = fmaxf(m, mx);
;       float mn = m;
;       if (__builtin_amdgcn_ballot_w64((mcand - m) > 8.f) != 0ull) {
;         mn = mcand;
;         const float alpha = __builtin_amdgcn_exp2f(m - mn);
;         m = mn;
;         l *= alpha;
; #pragma unroll
;         for (int i = 0; i < 16; ++i) { oacc[0][i] *= alpha; oacc[1][i] *= alpha; }
;       }
.LBB0_394:
	s_or_b64 exec, exec, s[62:63]
	v_max_f32_e32 v163, v49, v49
	v_max_f32_e32 v164, v48, v48
	v_max_f32_e32 v163, v164, v163
	v_max3_f32 v163, v163, v50, v51
	v_max3_f32 v163, v163, v52, v53
	v_max3_f32 v163, v163, v54, v55
	v_max3_f32 v163, v163, v56, v57
	v_max3_f32 v163, v163, v58, v59
	v_max3_f32 v163, v163, v60, v61
	v_max3_f32 v163, v163, v62, v63
	v_max3_f32 v163, v163, v32, v33
	v_max3_f32 v163, v163, v34, v35
	v_max3_f32 v163, v163, v36, v37
	v_max3_f32 v163, v163, v38, v39
	v_max3_f32 v163, v163, v40, v41
	v_max3_f32 v163, v163, v42, v43
	v_max3_f32 v163, v163, v44, v45
	v_max3_f32 v163, v163, v46, v47
	v_mov_b32_e32 v164, v163
	s_nop 1
	v_permlane32_swap_b32_e32 v163, v164
	v_max3_f32 v163, v133, v163, v164
	v_sub_f32_e32 v164, v163, v133
	v_cmp_lt_f32_e32 vcc, s74, v164
	s_cbranch_vccz .LBB0_403
	v_sub_f32_e32 v133, v133, v163
	v_exp_f32_e32 v164, v133
	v_mov_b32_e32 v133, v163
	v_pk_mul_f32 v[30:31], v[30:31], v[164:165] op_sel_hi:[1,0]
	v_pk_mul_f32 v[28:29], v[28:29], v[164:165] op_sel_hi:[1,0]
	v_pk_mul_f32 v[26:27], v[26:27], v[164:165] op_sel_hi:[1,0]
	v_pk_mul_f32 v[24:25], v[24:25], v[164:165] op_sel_hi:[1,0]
	v_pk_mul_f32 v[22:23], v[22:23], v[164:165] op_sel_hi:[1,0]
	v_pk_mul_f32 v[20:21], v[20:21], v[164:165] op_sel_hi:[1,0]
	v_pk_mul_f32 v[18:19], v[18:19], v[164:165] op_sel_hi:[1,0]
	v_pk_mul_f32 v[16:17], v[16:17], v[164:165] op_sel_hi:[1,0]
	v_pk_mul_f32 v[14:15], v[14:15], v[164:165] op_sel_hi:[1,0]
	v_pk_mul_f32 v[12:13], v[12:13], v[164:165] op_sel_hi:[1,0]
	v_pk_mul_f32 v[10:11], v[10:11], v[164:165] op_sel_hi:[1,0]
	v_pk_mul_f32 v[8:9], v[8:9], v[164:165] op_sel_hi:[1,0]
	v_pk_mul_f32 v[6:7], v[6:7], v[164:165] op_sel_hi:[1,0]
	v_pk_mul_f32 v[4:5], v[4:5], v[164:165] op_sel_hi:[1,0]
	v_pk_mul_f32 v[2:3], v[2:3], v[164:165] op_sel_hi:[1,0]
	v_pk_mul_f32 v[0:1], v[0:1], v[164:165] op_sel_hi:[1,0]
	v_mul_f32_e32 v162, v162, v164
